# prep Kfull jobs (layer-1 prep copy): the 18 later LDS reads of each dot-loop trip issued with the first group, one wait per trip
# speedup vs baseline: 1.0074x; 1.0008x over previous
.LBB0_87:
	ds_read2_b32 v[28:29], v5 offset1:16
	v_add_u32_e32 v27, 0x1000, v5
	v_add_u32_e32 v26, s1, v4
	ds_read2_b32 v[22:23], v27 offset1:16
	ds_read_b128 v[6:9], v26
	ds_read_b128 v[10:13], v26 offset:16
	ds_read_b128 v[14:17], v26 offset:32
	ds_read_b128 v[18:21], v26 offset:48
	ds_read2_b32 v[30:31], v5 offset0:32 offset1:48
	ds_read2_b32 v[34:35], v27 offset0:32 offset1:48
	ds_read2_b32 v[36:37], v5 offset0:64 offset1:80
	ds_read2_b32 v[38:39], v27 offset0:64 offset1:80
	ds_read2_b32 v[40:41], v5 offset0:96 offset1:112
	ds_read2_b32 v[42:43], v27 offset0:96 offset1:112
	ds_read2_b32 v[44:45], v5 offset0:128 offset1:144
	ds_read2_b32 v[46:47], v27 offset0:128 offset1:144
	ds_read_b128 v[48:51], v26 offset:64
	ds_read2_b32 v[52:53], v5 offset0:160 offset1:176
	ds_read2_b32 v[54:55], v27 offset0:160 offset1:176
	ds_read_b128 v[56:59], v26 offset:80
	ds_read2_b32 v[60:61], v5 offset0:192 offset1:208
	ds_read2_b32 v[62:63], v27 offset0:192 offset1:208
	ds_read_b128 v[64:67], v26 offset:96
	ds_read2_b32 v[68:69], v5 offset0:224 offset1:240
	ds_read2_b32 v[70:71], v27 offset0:224 offset1:240
	ds_read_b128 v[72:75], v26 offset:112
	s_waitcnt lgkmcnt(0)
	v_mov_b32_e32 v25, v22
	v_mov_b32_e32 v24, v28
	v_pk_mul_f32 v[6:7], v[6:7], v[24:25]
	v_mov_b32_e32 v22, v29
	v_sub_f32_e32 v6, v6, v7
	v_add_f32_e32 v2, v2, v6
	v_pk_mul_f32 v[6:7], v[8:9], v[22:23]
	s_addk_i32 s1, 0x80
	v_sub_f32_e32 v6, v6, v7
	v_add_f32_e32 v2, v2, v6
	v_mov_b32_e32 v22, v30
	v_mov_b32_e32 v23, v31
	v_mov_b32_e32 v6, v34
	v_mov_b32_e32 v7, v35
	s_cmpk_lg_i32 s1, 0x200
	v_mov_b32_e32 v8, v22
	v_mov_b32_e32 v9, v6
	v_pk_mul_f32 v[8:9], v[10:11], v[8:9]
	s_nop 0
	v_sub_f32_e32 v6, v8, v9
	v_add_f32_e32 v2, v2, v6
	v_mov_b32_e32 v6, v23
	v_pk_mul_f32 v[6:7], v[12:13], v[6:7]
	s_nop 0
	v_sub_f32_e32 v6, v6, v7
	v_add_f32_e32 v2, v2, v6
	v_mov_b32_e32 v10, v36
	v_mov_b32_e32 v11, v37
	v_mov_b32_e32 v6, v38
	v_mov_b32_e32 v7, v39
	v_mov_b32_e32 v8, v10
	v_mov_b32_e32 v9, v6
	v_pk_mul_f32 v[8:9], v[14:15], v[8:9]
	s_nop 0
	v_sub_f32_e32 v6, v8, v9
	v_add_f32_e32 v2, v2, v6
	v_mov_b32_e32 v6, v11
	v_pk_mul_f32 v[6:7], v[16:17], v[6:7]
	s_nop 0
	v_sub_f32_e32 v6, v6, v7
	v_add_f32_e32 v2, v2, v6
	v_mov_b32_e32 v10, v40
	v_mov_b32_e32 v11, v41
	v_mov_b32_e32 v6, v42
	v_mov_b32_e32 v7, v43
	v_mov_b32_e32 v8, v10
	v_mov_b32_e32 v9, v6
	v_pk_mul_f32 v[8:9], v[18:19], v[8:9]
	s_nop 0
	v_sub_f32_e32 v6, v8, v9
	v_add_f32_e32 v2, v2, v6
	v_mov_b32_e32 v6, v11
	v_pk_mul_f32 v[6:7], v[20:21], v[6:7]
	s_nop 0
	v_sub_f32_e32 v6, v6, v7
	v_add_f32_e32 v2, v2, v6
	v_mov_b32_e32 v14, v44
	v_mov_b32_e32 v15, v45
	v_mov_b32_e32 v10, v46
	v_mov_b32_e32 v11, v47
	v_mov_b32_e32 v6, v48
	v_mov_b32_e32 v7, v49
	v_mov_b32_e32 v8, v50
	v_mov_b32_e32 v9, v51
	v_mov_b32_e32 v12, v14
	v_mov_b32_e32 v13, v10
	v_pk_mul_f32 v[6:7], v[6:7], v[12:13]
	v_mov_b32_e32 v10, v15
	v_sub_f32_e32 v6, v6, v7
	v_add_f32_e32 v2, v2, v6
	v_pk_mul_f32 v[6:7], v[8:9], v[10:11]
	s_nop 0
	v_sub_f32_e32 v6, v6, v7
	v_add_f32_e32 v2, v2, v6
	v_mov_b32_e32 v14, v52
	v_mov_b32_e32 v15, v53
	v_mov_b32_e32 v10, v54
	v_mov_b32_e32 v11, v55
	v_mov_b32_e32 v6, v56
	v_mov_b32_e32 v7, v57
	v_mov_b32_e32 v8, v58
	v_mov_b32_e32 v9, v59
	v_mov_b32_e32 v12, v14
	v_mov_b32_e32 v13, v10
	v_pk_mul_f32 v[6:7], v[6:7], v[12:13]
	v_mov_b32_e32 v10, v15
	v_sub_f32_e32 v6, v6, v7
	v_add_f32_e32 v2, v2, v6
	v_pk_mul_f32 v[6:7], v[8:9], v[10:11]
	s_nop 0
	v_sub_f32_e32 v6, v6, v7
	v_add_f32_e32 v2, v2, v6
	v_mov_b32_e32 v14, v60
	v_mov_b32_e32 v15, v61
	v_mov_b32_e32 v10, v62
	v_mov_b32_e32 v11, v63
	v_mov_b32_e32 v6, v64
	v_mov_b32_e32 v7, v65
	v_mov_b32_e32 v8, v66
	v_mov_b32_e32 v9, v67
	v_mov_b32_e32 v12, v14
	v_mov_b32_e32 v13, v10
	v_pk_mul_f32 v[6:7], v[6:7], v[12:13]
	v_mov_b32_e32 v10, v15
	v_sub_f32_e32 v6, v6, v7
	v_add_f32_e32 v2, v2, v6
	v_pk_mul_f32 v[6:7], v[8:9], v[10:11]
	s_nop 0
	v_sub_f32_e32 v6, v6, v7
	v_add_f32_e32 v2, v2, v6
	v_mov_b32_e32 v14, v68
	v_mov_b32_e32 v15, v69
	v_mov_b32_e32 v10, v70
	v_mov_b32_e32 v11, v71
	v_mov_b32_e32 v6, v72
	v_mov_b32_e32 v7, v73
	v_mov_b32_e32 v8, v74
	v_mov_b32_e32 v9, v75
	v_add_u32_e32 v5, 0x400, v5
	v_mov_b32_e32 v12, v14
	v_mov_b32_e32 v13, v10
	v_pk_mul_f32 v[6:7], v[6:7], v[12:13]
	v_mov_b32_e32 v10, v15
	v_sub_f32_e32 v6, v6, v7
	v_add_f32_e32 v2, v2, v6
	v_pk_mul_f32 v[6:7], v[8:9], v[10:11]
	s_nop 0
	v_sub_f32_e32 v6, v6, v7
	v_add_f32_e32 v2, v2, v6
	s_cbranch_scc1 .LBB0_87

.LBB0_90:
	ds_read2_b32 v[28:29], v4 offset1:16
	v_add_u32_e32 v26, 0x1000, v4
	v_add_u32_e32 v5, s1, v3
	ds_read2_b32 v[22:23], v26 offset1:16
	ds_read_b128 v[6:9], v5
	ds_read_b128 v[10:13], v5 offset:16
	ds_read_b128 v[14:17], v5 offset:32
	ds_read_b128 v[18:21], v5 offset:48
	ds_read2_b32 v[30:31], v4 offset0:32 offset1:48
	ds_read2_b32 v[34:35], v26 offset0:32 offset1:48
	ds_read2_b32 v[36:37], v4 offset0:64 offset1:80
	ds_read2_b32 v[38:39], v26 offset0:64 offset1:80
	ds_read2_b32 v[40:41], v4 offset0:96 offset1:112
	ds_read2_b32 v[42:43], v26 offset0:96 offset1:112
	ds_read2_b32 v[44:45], v4 offset0:128 offset1:144
	ds_read2_b32 v[46:47], v26 offset0:128 offset1:144
	ds_read_b128 v[48:51], v5 offset:64
	ds_read2_b32 v[52:53], v4 offset0:160 offset1:176
	ds_read2_b32 v[54:55], v26 offset0:160 offset1:176
	ds_read_b128 v[56:59], v5 offset:80
	ds_read2_b32 v[60:61], v4 offset0:192 offset1:208
	ds_read2_b32 v[62:63], v26 offset0:192 offset1:208
	ds_read_b128 v[64:67], v5 offset:96
	ds_read2_b32 v[68:69], v4 offset0:224 offset1:240
	ds_read2_b32 v[70:71], v26 offset0:224 offset1:240
	ds_read_b128 v[72:75], v5 offset:112
	s_waitcnt lgkmcnt(0)
	v_mov_b32_e32 v25, v22
	v_mov_b32_e32 v24, v28
	v_pk_mul_f32 v[6:7], v[6:7], v[24:25]
	v_mov_b32_e32 v22, v29
	v_sub_f32_e32 v6, v6, v7
	v_add_f32_e32 v2, v2, v6
	v_pk_mul_f32 v[6:7], v[8:9], v[22:23]
	s_addk_i32 s1, 0x80
	v_sub_f32_e32 v6, v6, v7
	v_add_f32_e32 v2, v2, v6
	v_mov_b32_e32 v22, v30
	v_mov_b32_e32 v23, v31
	v_mov_b32_e32 v6, v34
	v_mov_b32_e32 v7, v35
	s_cmpk_lg_i32 s1, 0x200
	v_mov_b32_e32 v8, v22
	v_mov_b32_e32 v9, v6
	v_pk_mul_f32 v[8:9], v[10:11], v[8:9]
	s_nop 0
	v_sub_f32_e32 v6, v8, v9
	v_add_f32_e32 v2, v2, v6
	v_mov_b32_e32 v6, v23
	v_pk_mul_f32 v[6:7], v[12:13], v[6:7]
	s_nop 0
	v_sub_f32_e32 v6, v6, v7
	v_add_f32_e32 v2, v2, v6
	v_mov_b32_e32 v10, v36
	v_mov_b32_e32 v11, v37
	v_mov_b32_e32 v6, v38
	v_mov_b32_e32 v7, v39
	v_mov_b32_e32 v8, v10
	v_mov_b32_e32 v9, v6
	v_pk_mul_f32 v[8:9], v[14:15], v[8:9]
	s_nop 0
	v_sub_f32_e32 v6, v8, v9
	v_add_f32_e32 v2, v2, v6
	v_mov_b32_e32 v6, v11
	v_pk_mul_f32 v[6:7], v[16:17], v[6:7]
	s_nop 0
	v_sub_f32_e32 v6, v6, v7
	v_add_f32_e32 v2, v2, v6
	v_mov_b32_e32 v10, v40
	v_mov_b32_e32 v11, v41
	v_mov_b32_e32 v6, v42
	v_mov_b32_e32 v7, v43
	v_mov_b32_e32 v8, v10
	v_mov_b32_e32 v9, v6
	v_pk_mul_f32 v[8:9], v[18:19], v[8:9]
	s_nop 0
	v_sub_f32_e32 v6, v8, v9
	v_add_f32_e32 v2, v2, v6
	v_mov_b32_e32 v6, v11
	v_pk_mul_f32 v[6:7], v[20:21], v[6:7]
	s_nop 0
	v_sub_f32_e32 v6, v6, v7
	v_add_f32_e32 v2, v2, v6
	v_mov_b32_e32 v14, v44
	v_mov_b32_e32 v15, v45
	v_mov_b32_e32 v10, v46
	v_mov_b32_e32 v11, v47
	v_mov_b32_e32 v6, v48
	v_mov_b32_e32 v7, v49
	v_mov_b32_e32 v8, v50
	v_mov_b32_e32 v9, v51
	v_mov_b32_e32 v12, v14
	v_mov_b32_e32 v13, v10
	v_pk_mul_f32 v[6:7], v[6:7], v[12:13]
	v_mov_b32_e32 v10, v15
	v_sub_f32_e32 v6, v6, v7
	v_add_f32_e32 v2, v2, v6
	v_pk_mul_f32 v[6:7], v[8:9], v[10:11]
	s_nop 0
	v_sub_f32_e32 v6, v6, v7
	v_add_f32_e32 v2, v2, v6
	v_mov_b32_e32 v14, v52
	v_mov_b32_e32 v15, v53
	v_mov_b32_e32 v10, v54
	v_mov_b32_e32 v11, v55
	v_mov_b32_e32 v6, v56
	v_mov_b32_e32 v7, v57
	v_mov_b32_e32 v8, v58
	v_mov_b32_e32 v9, v59
	v_mov_b32_e32 v12, v14
	v_mov_b32_e32 v13, v10
	v_pk_mul_f32 v[6:7], v[6:7], v[12:13]
	v_mov_b32_e32 v10, v15
	v_sub_f32_e32 v6, v6, v7
	v_add_f32_e32 v2, v2, v6
	v_pk_mul_f32 v[6:7], v[8:9], v[10:11]
	s_nop 0
	v_sub_f32_e32 v6, v6, v7
	v_add_f32_e32 v2, v2, v6
	v_mov_b32_e32 v14, v60
	v_mov_b32_e32 v15, v61
	v_mov_b32_e32 v10, v62
	v_mov_b32_e32 v11, v63
	v_mov_b32_e32 v6, v64
	v_mov_b32_e32 v7, v65
	v_mov_b32_e32 v8, v66
	v_mov_b32_e32 v9, v67
	v_mov_b32_e32 v12, v14
	v_mov_b32_e32 v13, v10
	v_pk_mul_f32 v[6:7], v[6:7], v[12:13]
	v_mov_b32_e32 v10, v15
	v_sub_f32_e32 v6, v6, v7
	v_add_f32_e32 v2, v2, v6
	v_pk_mul_f32 v[6:7], v[8:9], v[10:11]
	s_nop 0
	v_sub_f32_e32 v6, v6, v7
	v_add_f32_e32 v2, v2, v6
	v_mov_b32_e32 v14, v68
	v_mov_b32_e32 v15, v69
	v_mov_b32_e32 v10, v70
	v_mov_b32_e32 v11, v71
	v_mov_b32_e32 v6, v72
	v_mov_b32_e32 v7, v73
	v_mov_b32_e32 v8, v74
	v_mov_b32_e32 v9, v75
	v_add_u32_e32 v4, 0x400, v4
	v_mov_b32_e32 v12, v14
	v_mov_b32_e32 v13, v10
	v_pk_mul_f32 v[6:7], v[6:7], v[12:13]
	v_mov_b32_e32 v10, v15
	v_sub_f32_e32 v5, v6, v7
	v_pk_mul_f32 v[6:7], v[8:9], v[10:11]
	v_add_f32_e32 v2, v2, v5
	v_sub_f32_e32 v5, v6, v7
	v_add_f32_e32 v2, v2, v5
	s_cbranch_scc1 .LBB0_90
